# norm phases: non-temporal (nt) hint on the residual-row loads (read once per phase), on top of v57
# baseline (speedup 1.0000x reference)
; DI void phase_norm(const Params& p, int layer, int which, bool from_input, bool skipctx) {
;     ...
;     for (int u = 0; u < 2; ++u) {
;       const float* xr = from_input ? xrow_in(p, t0 + u) : xrow_ws(p, t0 + u);
; #pragma unroll
;       for (int i = 0; i < 4; ++i) { v[u][i] = *(const float4*)(xr + (i * 64 + lane) * 4); }
;     }
; #pragma unroll
;     for (int u = 0; u < 2; ++u) {
; #pragma unroll
;       for (int i = 0; i < 4; ++i) ss[u] += v[u][i].x * v[u][i].x + v[u][i].y * v[u][i].y + v[u][i].z * v[u][i].z + v[u][i].w * v[u][i].w;
;       ss[u] = wave_sum(ss[u]);
;     }
; #pragma unroll
;     for (int i = 0; i < 4; ++i) {
;       const int k = (i * 64 + lane) * 4;
; #pragma unroll
;       for (int u = 0; u < 2; ++u) {
;         const float rstd = rsqrtf(ss[u] * (1.f / 1024.f) + EPS);
;         float o0 = v[u][i].x * rstd * gg[i].x * (1.f + c4[i].x) + s4[i].x, o1 = v[u][i].y * rstd * gg[i].y * (1.f + c4[i].y) + s4[i].y;
;         float o2 = v[u][i].z * rstd * gg[i].z * (1.f + c4[i].z) + s4[i].z, o3 = v[u][i].w * rstd * gg[i].w * (1.f + c4[i].w) + s4[i].w;
.LBB0_55:
	v_ashrrev_i32_e32 v49, 31, v48
	v_cndmask_b32_e64 v54, 24, 20, s[0:1]
	v_lshlrev_b64 v[48:49], v54, v[48:49]
	v_lshl_add_u64 v[48:49], v[52:53], 0, v[48:49]
	v_lshlrev_b64 v[50:51], 12, v[50:51]
	v_lshl_add_u64 v[48:49], v[48:49], 0, v[50:51]
	v_lshl_add_u64 v[56:57], v[48:49], 0, v[220:221]
	global_load_dwordx4 v[48:51], v[56:57], off nt
	global_load_dwordx4 v[52:55], v[56:57], off offset:1024 nt
	global_load_dwordx4 v[60:63], v[56:57], off offset:2048 nt
	s_nop 0
	global_load_dwordx4 v[56:59], v[56:57], off offset:3072 nt
	s_waitcnt vmcnt(7)
	v_mov_b32_e32 v96, v77
	s_waitcnt vmcnt(6)
	v_mov_b32_e32 v97, v73
	s_waitcnt vmcnt(5)
	v_mov_b32_e32 v104, v69
	s_waitcnt vmcnt(4)
	v_mov_b32_e32 v105, v65
	v_mov_b32_e32 v94, v76
	v_mov_b32_e32 v95, v72
	v_mov_b32_e32 v102, v68
	v_mov_b32_e32 v103, v64
	v_pk_mul_f32 v[96:97], v[96:97], v[96:97]
	v_pk_mul_f32 v[104:105], v[104:105], v[104:105]
	v_mov_b32_e32 v106, v70
	v_mov_b32_e32 v107, v66
	v_pk_fma_f32 v[94:95], v[94:95], v[94:95], v[96:97]
	v_pk_fma_f32 v[96:97], v[102:103], v[102:103], v[104:105]
	v_mov_b32_e32 v112, v71
	v_mov_b32_e32 v113, v67
	v_pk_fma_f32 v[96:97], v[106:107], v[106:107], v[96:97]
	v_mov_b32_e32 v98, v78
	v_pk_fma_f32 v[96:97], v[112:113], v[112:113], v[96:97]
	v_mov_b32_e32 v99, v74
	v_mov_b32_e32 v100, v79
	v_mov_b32_e32 v101, v75
	v_pk_fma_f32 v[94:95], v[98:99], v[98:99], v[94:95]
	s_mov_b32 s0, 0x3a800000
	v_pk_fma_f32 v[94:95], v[100:101], v[100:101], v[94:95]
	v_mov_b32_e32 v101, v96
	v_mov_b32_e32 v99, v94
	v_ashrrev_i32_e32 v81, 31, v80
	v_ashrrev_i32_e32 v93, 31, v92
	v_lshlrev_b64 v[92:93], 11, v[92:93]
	v_lshl_add_u64 v[120:121], v[90:91], 0, v[92:93]
	v_lshlrev_b32_e32 v220, 1, v84
	s_waitcnt vmcnt(3)
	v_mov_b32_e32 v112, v49
	s_waitcnt vmcnt(2)
	v_mov_b32_e32 v113, v53
	v_mov_b32_e32 v106, v48
	v_mov_b32_e32 v107, v52
	v_pk_mul_f32 v[112:113], v[112:113], v[112:113]
	v_mov_b32_e32 v102, v50
	v_pk_fma_f32 v[106:107], v[106:107], v[106:107], v[112:113]
	s_waitcnt vmcnt(1)
	v_mov_b32_e32 v112, v61
	s_waitcnt vmcnt(0)
	v_mov_b32_e32 v113, v57
	v_mov_b32_e32 v103, v54
	v_mov_b32_e32 v118, v60
	v_mov_b32_e32 v119, v56
	v_pk_mul_f32 v[112:113], v[112:113], v[112:113]
	v_mov_b32_e32 v104, v51
	v_mov_b32_e32 v105, v55
	v_mov_b32_e32 v114, v62
	v_mov_b32_e32 v115, v58
	v_pk_fma_f32 v[112:113], v[118:119], v[118:119], v[112:113]
	v_pk_fma_f32 v[102:103], v[102:103], v[102:103], v[106:107]
	v_mov_b32_e32 v116, v63
	v_mov_b32_e32 v117, v59
	v_pk_fma_f32 v[106:107], v[114:115], v[114:115], v[112:113]
	v_pk_fma_f32 v[102:103], v[104:105], v[104:105], v[102:103]
	v_pk_fma_f32 v[104:105], v[116:117], v[116:117], v[106:107]
	v_mov_b32_e32 v98, v102
	v_mov_b32_e32 v94, v103
	v_mov_b32_e32 v100, v104
	v_pk_add_f32 v[94:95], v[98:99], v[94:95]
	v_mov_b32_e32 v96, v105
	v_pk_add_f32 v[94:95], v[94:95], v[100:101]
	v_lshlrev_b64 v[114:115], 11, v[80:81]
	v_pk_add_f32 v[94:95], v[94:95], v[96:97]
	ds_bpermute_b32 v97, v83, v95
	ds_bpermute_b32 v96, v83, v94
	v_pk_add_f32 v[102:103], v[28:29], 1.0 op_sel_hi:[1,0]
	v_pk_add_f32 v[104:105], v[30:31], 1.0 op_sel_hi:[1,0]
	v_add_u32_e32 v80, s91, v80
	s_waitcnt lgkmcnt(0)
	v_pk_add_f32 v[94:95], v[94:95], v[96:97]
	ds_bpermute_b32 v97, v85, v95
	ds_bpermute_b32 v96, v85, v94
	s_waitcnt lgkmcnt(0)
	v_pk_add_f32 v[94:95], v[94:95], v[96:97]
	ds_bpermute_b32 v97, v87, v95
	ds_bpermute_b32 v96, v87, v94
	s_waitcnt lgkmcnt(0)
	v_pk_add_f32 v[94:95], v[94:95], v[96:97]
	ds_bpermute_b32 v97, v89, v95
	ds_bpermute_b32 v96, v89, v94
	s_waitcnt lgkmcnt(0)
	v_pk_add_f32 v[98:99], v[94:95], v[96:97]
	ds_bpermute_b32 v101, v108, v99
	ds_bpermute_b32 v100, v108, v98
	v_pk_add_f32 v[94:95], v[20:21], 1.0 op_sel_hi:[1,0]
	v_pk_add_f32 v[96:97], v[22:23], 1.0 op_sel_hi:[1,0]
	s_waitcnt lgkmcnt(0)
	v_pk_add_f32 v[106:107], v[98:99], v[100:101]
	ds_bpermute_b32 v113, v109, v107
	ds_bpermute_b32 v112, v109, v106
	v_pk_add_f32 v[100:101], v[36:37], 1.0 op_sel_hi:[1,0]
	v_pk_add_f32 v[98:99], v[38:39], 1.0 op_sel_hi:[1,0]
	s_waitcnt lgkmcnt(0)
; DI unsigned pk2(float a, float b) { f2_t v = {a, b}; bf2_t r = __builtin_convertvector(v, bf2_t); return __builtin_bit_cast(unsigned, r); }
; DI void phase_norm(const Params& p, int layer, int which, bool from_input, bool skipctx) {
;     ...
;       ss[u] = wave_sum(ss[u]);
;     }
; #pragma unroll
;     for (int i = 0; i < 4; ++i) {
;       const int k = (i * 64 + lane) * 4;
; #pragma unroll
;       for (int u = 0; u < 2; ++u) {
;         const float rstd = rsqrtf(ss[u] * (1.f / 1024.f) + EPS);
;         float o0 = v[u][i].x * rstd * gg[i].x * (1.f + c4[i].x) + s4[i].x, o1 = v[u][i].y * rstd * gg[i].y * (1.f + c4[i].y) + s4[i].y;
;         float o2 = v[u][i].z * rstd * gg[i].z * (1.f + c4[i].z) + s4[i].z, o3 = v[u][i].w * rstd * gg[i].w * (1.f + c4[i].w) + s4[i].w;
;         uint2 o; o.x = pk2(o0, o1); o.y = pk2(o2, o3);
;         *(uint2*)(H + (size_t)(t0 + u) * 1024 + k) = o;
;       }
;     }
	v_pk_add_f32 v[106:107], v[106:107], v[112:113]
	s_nop 0
	v_pk_fma_f32 v[112:113], v[106:107], s[0:1], v[196:197] op_sel_hi:[1,0,0]
	v_readlane_b32 s0, v251, 55
	v_mul_f32_e32 v106, 0x4b800000, v113
	v_cmp_gt_f32_e32 vcc, s81, v113
	v_readlane_b32 s1, v251, 56
	s_nop 0
	v_cndmask_b32_e32 v106, v113, v106, vcc
	v_rsq_f32_e32 v111, v106
	v_pk_add_f32 v[106:107], v[44:45], 1.0 op_sel_hi:[1,0]
	v_mul_f32_e32 v81, 0x45800000, v111
	v_cndmask_b32_e32 v116, v111, v81, vcc
	v_mul_f32_e32 v81, 0x4b800000, v112
	v_cmp_gt_f32_e32 vcc, s81, v112
	v_pk_mul_f32 v[118:119], v[68:69], v[116:117] op_sel_hi:[1,0]
	v_pk_mul_f32 v[70:71], v[70:71], v[116:117] op_sel_hi:[1,0]
	v_cndmask_b32_e32 v81, v112, v81, vcc
	v_pk_mul_f32 v[112:113], v[8:9], v[118:119]
	v_pk_mul_f32 v[70:71], v[10:11], v[70:71]
	v_rsq_f32_e32 v81, v81
	v_pk_mul_f32 v[68:69], v[64:65], v[116:117] op_sel_hi:[1,0]
	v_pk_mul_f32 v[64:65], v[66:67], v[116:117] op_sel_hi:[1,0]
	v_pk_fma_f32 v[112:113], v[100:101], v[112:113], v[32:33]
	v_pk_fma_f32 v[70:71], v[98:99], v[70:71], v[34:35]
	v_cvt_pk_bf16_f32 v112, v112, v113
	v_cvt_pk_bf16_f32 v113, v70, v71
	v_pk_add_f32 v[70:71], v[46:47], 1.0 op_sel_hi:[1,0]
	v_pk_mul_f32 v[68:69], v[12:13], v[68:69]
	v_pk_mul_f32 v[64:65], v[14:15], v[64:65]
	v_pk_fma_f32 v[68:69], v[106:107], v[68:69], v[40:41]
	v_pk_fma_f32 v[64:65], v[70:71], v[64:65], v[42:43]
	v_cvt_pk_bf16_f32 v68, v68, v69
	v_cvt_pk_bf16_f32 v69, v64, v65
	v_mul_f32_e32 v64, 0x45800000, v81
	v_cndmask_b32_e32 v64, v81, v64, vcc
	v_pk_mul_f32 v[76:77], v[76:77], v[116:117] op_sel_hi:[1,0]
	v_pk_mul_f32 v[78:79], v[78:79], v[116:117] op_sel_hi:[1,0]
	v_pk_mul_f32 v[48:49], v[48:49], v[64:65] op_sel_hi:[1,0]
	v_pk_mul_f32 v[50:51], v[50:51], v[64:65] op_sel_hi:[1,0]
	v_pk_mul_f32 v[72:73], v[72:73], v[116:117] op_sel_hi:[1,0]
	v_pk_mul_f32 v[74:75], v[74:75], v[116:117] op_sel_hi:[1,0]
	v_pk_mul_f32 v[76:77], v[0:1], v[76:77]
	v_pk_mul_f32 v[78:79], v[2:3], v[78:79]
	v_pk_mul_f32 v[48:49], v[0:1], v[48:49]
	v_pk_mul_f32 v[50:51], v[2:3], v[50:51]
	v_pk_fma_f32 v[76:77], v[94:95], v[76:77], v[16:17]
	v_pk_fma_f32 v[78:79], v[96:97], v[78:79], v[18:19]
	v_pk_mul_f32 v[72:73], v[4:5], v[72:73]
	v_pk_mul_f32 v[74:75], v[6:7], v[74:75]
	v_pk_fma_f32 v[48:49], v[94:95], v[48:49], v[16:17]
	v_pk_fma_f32 v[50:51], v[96:97], v[50:51], v[18:19]
	v_lshl_add_u64 v[116:117], v[90:91], 0, v[114:115]
	v_lshl_add_u64 v[114:115], s[0:1], 0, v[114:115]
	v_cvt_pk_bf16_f32 v76, v76, v77
	v_cvt_pk_bf16_f32 v77, v78, v79
	v_pk_fma_f32 v[72:73], v[102:103], v[72:73], v[24:25]
	v_pk_fma_f32 v[74:75], v[104:105], v[74:75], v[26:27]
	v_cvt_pk_bf16_f32 v48, v48, v49
	v_cvt_pk_bf16_f32 v49, v50, v51
	v_lshl_add_u64 v[78:79], v[114:115], 0, v[220:221]
	global_store_dwordx2 v[116:117], v[76:77], off
	v_cvt_pk_bf16_f32 v72, v72, v73
	v_cvt_pk_bf16_f32 v73, v74, v75
	global_store_dwordx2 v[120:121], v[48:49], off
	global_store_dwordx2 v[78:79], v[72:73], off
	v_pk_mul_f32 v[48:49], v[52:53], v[64:65] op_sel_hi:[1,0]
	v_pk_mul_f32 v[50:51], v[54:55], v[64:65] op_sel_hi:[1,0]
	v_pk_mul_f32 v[48:49], v[4:5], v[48:49]
	v_pk_mul_f32 v[50:51], v[6:7], v[50:51]
	v_lshl_add_u64 v[66:67], s[0:1], 0, v[92:93]
	v_pk_fma_f32 v[48:49], v[102:103], v[48:49], v[24:25]
	v_pk_fma_f32 v[50:51], v[104:105], v[50:51], v[26:27]
	v_lshl_add_u64 v[76:77], v[66:67], 0, v[220:221]
	v_lshlrev_b32_e32 v220, 1, v86
	v_cvt_pk_bf16_f32 v48, v48, v49
	v_cvt_pk_bf16_f32 v49, v50, v51
	v_lshl_add_u64 v[92:93], v[114:115], 0, v[220:221]
	global_store_dwordx2 v[76:77], v[48:49], off
	global_store_dwordx2 v[92:93], v[112:113], off
	v_pk_mul_f32 v[48:49], v[60:61], v[64:65] op_sel_hi:[1,0]
	v_pk_mul_f32 v[50:51], v[62:63], v[64:65] op_sel_hi:[1,0]
	v_pk_mul_f32 v[48:49], v[8:9], v[48:49]
	v_pk_mul_f32 v[50:51], v[10:11], v[50:51]
	v_pk_fma_f32 v[48:49], v[100:101], v[48:49], v[32:33]
	v_pk_fma_f32 v[50:51], v[98:99], v[50:51], v[34:35]
	v_lshl_add_u64 v[74:75], v[66:67], 0, v[220:221]
	v_lshlrev_b32_e32 v220, 1, v88
	v_cvt_pk_bf16_f32 v48, v48, v49
	v_cvt_pk_bf16_f32 v49, v50, v51
	v_lshl_add_u64 v[114:115], v[114:115], 0, v[220:221]
	global_store_dwordx2 v[74:75], v[48:49], off
	global_store_dwordx2 v[114:115], v[68:69], off
	v_pk_mul_f32 v[48:49], v[56:57], v[64:65] op_sel_hi:[1,0]
	v_pk_mul_f32 v[50:51], v[58:59], v[64:65] op_sel_hi:[1,0]
	v_pk_mul_f32 v[48:49], v[12:13], v[48:49]
	v_pk_mul_f32 v[50:51], v[14:15], v[50:51]
	s_mov_b32 s0, 0x87ff
	v_pk_fma_f32 v[48:49], v[106:107], v[48:49], v[40:41]
	v_pk_fma_f32 v[50:51], v[70:71], v[50:51], v[42:43]
	v_cmp_lt_i32_e32 vcc, s0, v80
	v_cvt_pk_bf16_f32 v48, v48, v49
	v_cvt_pk_bf16_f32 v49, v50, v51
	v_lshl_add_u64 v[50:51], v[66:67], 0, v[220:221]
	s_or_b64 s[38:39], vcc, s[38:39]
	global_store_dwordx2 v[50:51], v[48:49], off
	s_andn2_b64 exec, exec, s[38:39]
	s_cbranch_execz .LBB0_66

; DI void phase_norm(const Params& p, int layer, int which, bool from_input, bool skipctx) {
;     ...
;     float4 v[2][4]; float ss[2] = {0.f, 0.f};
; #pragma unroll
;     for (int u = 0; u < 2; ++u) {
;       const float* xr = from_input ? xrow_in(p, t0 + u) : xrow_ws(p, t0 + u);
; #pragma unroll
;       for (int i = 0; i < 4; ++i) { v[u][i] = *(const float4*)(xr + (i * 64 + lane) * 4); }
;     }
; #pragma unroll
;     for (int u = 0; u < 2; ++u) {
; #pragma unroll
;       for (int i = 0; i < 4; ++i) ss[u] += v[u][i].x * v[u][i].x + v[u][i].y * v[u][i].y + v[u][i].z * v[u][i].z + v[u][i].w * v[u][i].w;
;       ss[u] = wave_sum(ss[u]);
;     }
.LBB0_1791:
	s_or_b64 exec, exec, s[44:45]
	v_add_u32_e32 v92, 1, v80
	v_add_u32_e32 v54, 0xffffff00, v50
	v_mul_hi_i32 v58, v92, s51
	v_ashrrev_i32_e32 v49, 31, v48
	v_ashrrev_i32_e32 v51, 31, v50
	v_mov_b32_e32 v60, s93
	v_mov_b32_e32 v61, s83
	v_mov_b32_e32 v62, s92
	v_mov_b32_e32 v63, s29
	v_cndmask_b32_e32 v50, v54, v50, vcc
	v_cndmask_b32_e64 v54, 24, 20, vcc
	v_lshrrev_b32_e32 v59, 31, v58
	v_ashrrev_i32_e32 v58, 11, v58
	v_cndmask_b32_e32 v53, v60, v61, vcc
	v_cndmask_b32_e32 v52, v62, v63, vcc
	v_cndmask_b32_e32 v51, 0, v51, vcc
	v_lshlrev_b64 v[48:49], v54, v[48:49]
	v_add_u32_e32 v58, v58, v59
	v_lshl_add_u64 v[48:49], v[52:53], 0, v[48:49]
	v_lshlrev_b64 v[50:51], 12, v[50:51]
	v_mad_i32_i24 v64, v58, s80, v80
	v_lshl_add_u64 v[48:49], v[48:49], 0, v[50:51]
	v_add_u32_e32 v65, 1, v64
	v_lshl_add_u64 v[56:57], v[48:49], 0, v[220:221]
	v_cmp_gt_i32_e32 vcc, s50, v65
	global_load_dwordx4 v[48:51], v[56:57], off nt
	global_load_dwordx4 v[52:55], v[56:57], off offset:1024 nt
	v_ashrrev_i32_e32 v59, 31, v58
	global_load_dwordx4 v[68:71], v[56:57], off offset:2048 nt
	global_load_dwordx4 v[76:79], v[56:57], off offset:3072 nt
	v_cndmask_b32_e64 v56, 24, 20, vcc
	v_ashrrev_i32_e32 v66, 31, v65
	v_add_u32_e32 v64, 0xffffff01, v64
	v_lshlrev_b64 v[56:57], v56, v[58:59]
	v_cndmask_b32_e32 v59, v60, v61, vcc
	v_cndmask_b32_e32 v58, v62, v63, vcc
	v_cndmask_b32_e32 v61, 0, v66, vcc
	v_cndmask_b32_e32 v60, v64, v65, vcc
	v_lshl_add_u64 v[56:57], v[58:59], 0, v[56:57]
	v_lshlrev_b64 v[58:59], 12, v[60:61]
	v_lshl_add_u64 v[56:57], v[56:57], 0, v[58:59]
	v_lshl_add_u64 v[56:57], v[56:57], 0, v[220:221]
	global_load_dwordx4 v[72:75], v[56:57], off nt
	global_load_dwordx4 v[64:67], v[56:57], off offset:1024 nt
	global_load_dwordx4 v[60:63], v[56:57], off offset:2048 nt
	s_nop 0
	global_load_dwordx4 v[56:59], v[56:57], off offset:3072 nt
	v_cmp_lt_i32_e32 vcc, v224, v207
	v_readlane_b32 s0, v251, 55
	v_readlane_b32 s1, v251, 56
	v_cndmask_b32_e32 v81, v205, v224, vcc
	v_lshlrev_b32_e32 v81, 2, v81
	v_cmp_lt_i32_e32 vcc, v225, v207
	s_waitcnt vmcnt(12)
	v_pk_add_f32 v[110:111], v[24:25], 1.0 op_sel_hi:[1,0]
	s_waitcnt vmcnt(10)
	v_pk_add_f32 v[116:117], v[34:35], 1.0 op_sel_hi:[1,0]
	v_cndmask_b32_e32 v85, v205, v225, vcc
	v_lshlrev_b32_e32 v85, 2, v85
	v_cmp_lt_i32_e32 vcc, v193, v207
	v_pk_add_f32 v[118:119], v[32:33], 1.0 op_sel_hi:[1,0]
	s_waitcnt vmcnt(8)
	v_pk_add_f32 v[124:125], v[42:43], 1.0 op_sel_hi:[1,0]
	v_cndmask_b32_e32 v87, v205, v193, vcc
	v_lshlrev_b32_e32 v87, 2, v87
	v_cmp_lt_i32_e32 vcc, v197, v207
	v_lshlrev_b32_e32 v220, 1, v84
	s_waitcnt vmcnt(7)
	v_mov_b32_e32 v100, v49
	s_waitcnt vmcnt(6)
	v_mov_b32_e32 v101, v53
	s_waitcnt vmcnt(5)
	v_mov_b32_e32 v108, v69
	s_waitcnt vmcnt(4)
	v_mov_b32_e32 v109, v77
	v_mov_b32_e32 v98, v48
	v_mov_b32_e32 v99, v52
	v_mov_b32_e32 v106, v68
	v_mov_b32_e32 v107, v76
	v_pk_mul_f32 v[100:101], v[100:101], v[100:101]
	v_pk_mul_f32 v[108:109], v[108:109], v[108:109]
	v_mov_b32_e32 v94, v50
	v_mov_b32_e32 v95, v54
	v_mov_b32_e32 v102, v70
	v_mov_b32_e32 v103, v78
	v_pk_fma_f32 v[98:99], v[98:99], v[98:99], v[100:101]
	v_pk_fma_f32 v[100:101], v[106:107], v[106:107], v[108:109]
	s_waitcnt vmcnt(3)
	v_mov_b32_e32 v106, v73
	s_waitcnt vmcnt(2)
	v_mov_b32_e32 v107, v65
	v_mov_b32_e32 v96, v51
	v_mov_b32_e32 v97, v55
	v_pk_fma_f32 v[94:95], v[94:95], v[94:95], v[98:99]
	v_pk_fma_f32 v[98:99], v[102:103], v[102:103], v[100:101]
	v_mov_b32_e32 v102, v72
	v_mov_b32_e32 v103, v64
	v_pk_mul_f32 v[106:107], v[106:107], v[106:107]
	v_mov_b32_e32 v104, v71
	v_mov_b32_e32 v105, v79
	v_pk_fma_f32 v[94:95], v[96:97], v[96:97], v[94:95]
	v_mov_b32_e32 v96, v74
	v_mov_b32_e32 v97, v66
	v_pk_fma_f32 v[102:103], v[102:103], v[102:103], v[106:107]
	s_waitcnt vmcnt(1)
	v_mov_b32_e32 v106, v61
	s_waitcnt vmcnt(0)
	v_mov_b32_e32 v107, v57
	v_mov_b32_e32 v100, v75
	v_mov_b32_e32 v101, v67
	v_pk_fma_f32 v[96:97], v[96:97], v[96:97], v[102:103]
	v_pk_fma_f32 v[98:99], v[104:105], v[104:105], v[98:99]
	v_mov_b32_e32 v104, v60
	v_mov_b32_e32 v105, v56
	v_pk_mul_f32 v[106:107], v[106:107], v[106:107]
	v_pk_fma_f32 v[96:97], v[100:101], v[100:101], v[96:97]
	v_mov_b32_e32 v100, v62
	v_mov_b32_e32 v101, v58
	v_pk_fma_f32 v[104:105], v[104:105], v[104:105], v[106:107]
	v_mov_b32_e32 v102, v63
	v_mov_b32_e32 v103, v59
	v_pk_fma_f32 v[100:101], v[100:101], v[100:101], v[104:105]
	v_cndmask_b32_e32 v89, v205, v197, vcc
	v_pk_fma_f32 v[100:101], v[102:103], v[102:103], v[100:101]
	v_mov_b32_e32 v102, v96
	v_mov_b32_e32 v103, v94
	v_mov_b32_e32 v94, v97
	v_pk_add_f32 v[94:95], v[102:103], v[94:95]
	v_mov_b32_e32 v96, v100
	v_mov_b32_e32 v97, v98
	v_pk_add_f32 v[94:95], v[94:95], v[96:97]
	v_mov_b32_e32 v98, v101
	v_pk_add_f32 v[94:95], v[94:95], v[98:99]
	ds_bpermute_b32 v97, v81, v95
	ds_bpermute_b32 v96, v81, v94
	v_lshlrev_b32_e32 v89, 2, v89
	v_cmp_lt_i32_e32 vcc, v248, v207
	v_xor_b32_e32 v81, 1, v205
	v_pk_add_f32 v[98:99], v[18:19], 1.0 op_sel_hi:[1,0]
	s_waitcnt lgkmcnt(0)
	v_pk_add_f32 v[94:95], v[94:95], v[96:97]
	ds_bpermute_b32 v97, v85, v95
	ds_bpermute_b32 v96, v85, v94
	v_cndmask_b32_e32 v93, v205, v248, vcc
	v_lshlrev_b32_e32 v114, 2, v93
	v_cmp_lt_i32_e32 vcc, v81, v207
	v_ashrrev_i32_e32 v93, 31, v92
	s_waitcnt lgkmcnt(0)
; DI unsigned pk2(float a, float b) { f2_t v = {a, b}; bf2_t r = __builtin_convertvector(v, bf2_t); return __builtin_bit_cast(unsigned, r); }
; DI void phase_norm(const Params& p, int layer, int which, bool from_input, bool skipctx) {
;     ...
;       ss[u] = wave_sum(ss[u]);
;     }
; #pragma unroll
;     for (int i = 0; i < 4; ++i) {
;       const int k = (i * 64 + lane) * 4;
; #pragma unroll
;       for (int u = 0; u < 2; ++u) {
;         const float rstd = rsqrtf(ss[u] * (1.f / 1024.f) + EPS);
;         float o0 = v[u][i].x * rstd * gg[i].x * (1.f + c4[i].x) + s4[i].x, o1 = v[u][i].y * rstd * gg[i].y * (1.f + c4[i].y) + s4[i].y;
;         float o2 = v[u][i].z * rstd * gg[i].z * (1.f + c4[i].z) + s4[i].z, o3 = v[u][i].w * rstd * gg[i].w * (1.f + c4[i].w) + s4[i].w;
;         uint2 o; o.x = pk2(o0, o1); o.y = pk2(o2, o3);
;         *(uint2*)(H + (size_t)(t0 + u) * 1024 + k) = o;
;       }
;     }
	v_pk_add_f32 v[94:95], v[94:95], v[96:97]
	ds_bpermute_b32 v97, v87, v95
	ds_bpermute_b32 v96, v87, v94
	v_cndmask_b32_e32 v81, v205, v81, vcc
	v_lshlrev_b32_e32 v120, 2, v81
	v_ashrrev_i32_e32 v81, 31, v80
	v_lshlrev_b64 v[102:103], 11, v[80:81]
	s_waitcnt lgkmcnt(0)
	v_pk_add_f32 v[94:95], v[94:95], v[96:97]
	ds_bpermute_b32 v97, v89, v95
	ds_bpermute_b32 v96, v89, v94
	v_lshlrev_b64 v[92:93], 11, v[92:93]
	v_lshl_add_u64 v[104:105], v[90:91], 0, v[102:103]
	v_lshl_add_u64 v[106:107], v[90:91], 0, v[92:93]
	v_lshl_add_u64 v[102:103], s[0:1], 0, v[102:103]
	s_waitcnt lgkmcnt(0)
	v_pk_add_f32 v[94:95], v[94:95], v[96:97]
	ds_bpermute_b32 v97, v114, v95
	ds_bpermute_b32 v96, v114, v94
	v_lshl_add_u64 v[92:93], s[0:1], 0, v[92:93]
	s_mov_b32 s0, 0x3a800000
	v_pk_add_f32 v[100:101], v[16:17], 1.0 op_sel_hi:[1,0]
	v_pk_add_f32 v[108:109], v[26:27], 1.0 op_sel_hi:[1,0]
	s_waitcnt lgkmcnt(0)
	v_pk_add_f32 v[94:95], v[94:95], v[96:97]
	ds_bpermute_b32 v97, v120, v95
	ds_bpermute_b32 v96, v120, v94
	v_lshl_add_u64 v[112:113], v[102:103], 0, v[220:221]
	v_lshl_add_u64 v[114:115], v[92:93], 0, v[220:221]
	v_lshlrev_b32_e32 v220, 1, v86
	v_lshl_add_u64 v[120:121], v[102:103], 0, v[220:221]
	s_waitcnt lgkmcnt(0)
	v_pk_add_f32 v[94:95], v[94:95], v[96:97]
	v_pk_add_f32 v[96:97], v[40:41], 1.0 op_sel_hi:[1,0]
	v_pk_fma_f32 v[94:95], v[94:95], s[0:1], v[196:197] op_sel_hi:[1,0,0]
	v_lshl_add_u64 v[122:123], v[92:93], 0, v[220:221]
	v_mul_f32_e32 v81, 0x4b800000, v95
	v_cmp_gt_f32_e32 vcc, s81, v95
	v_lshlrev_b32_e32 v220, 1, v88
	v_lshl_add_u64 v[102:103], v[102:103], 0, v[220:221]
	v_cndmask_b32_e32 v81, v95, v81, vcc
	v_rsq_f32_e32 v81, v81
	s_nop 0
	v_mul_f32_e32 v85, 0x45800000, v81
	v_cndmask_b32_e32 v126, v81, v85, vcc
	v_pk_mul_f32 v[48:49], v[48:49], v[126:127] op_sel_hi:[1,0]
	v_pk_mul_f32 v[50:51], v[50:51], v[126:127] op_sel_hi:[1,0]
	v_pk_mul_f32 v[48:49], v[0:1], v[48:49]
	v_pk_mul_f32 v[50:51], v[2:3], v[50:51]
	v_pk_fma_f32 v[48:49], v[100:101], v[48:49], v[20:21]
	v_pk_fma_f32 v[50:51], v[98:99], v[50:51], v[22:23]
	v_cvt_pk_bf16_f32 v48, v48, v49
	v_cvt_pk_bf16_f32 v49, v50, v51
	v_pk_mul_f32 v[50:51], v[52:53], v[126:127] op_sel_hi:[1,0]
	v_pk_mul_f32 v[52:53], v[54:55], v[126:127] op_sel_hi:[1,0]
	v_pk_mul_f32 v[50:51], v[4:5], v[50:51]
	v_pk_mul_f32 v[52:53], v[6:7], v[52:53]
	v_pk_fma_f32 v[50:51], v[110:111], v[50:51], v[28:29]
	v_pk_fma_f32 v[52:53], v[108:109], v[52:53], v[30:31]
	v_cvt_pk_bf16_f32 v50, v50, v51
	v_cvt_pk_bf16_f32 v51, v52, v53
	v_pk_mul_f32 v[52:53], v[68:69], v[126:127] op_sel_hi:[1,0]
	v_pk_mul_f32 v[54:55], v[70:71], v[126:127] op_sel_hi:[1,0]
	v_mul_f32_e32 v70, 0x4b800000, v94
	v_cmp_gt_f32_e32 vcc, s81, v94
	v_pk_mul_f32 v[52:53], v[8:9], v[52:53]
	v_pk_mul_f32 v[54:55], v[10:11], v[54:55]
	v_cndmask_b32_e32 v70, v94, v70, vcc
	v_pk_fma_f32 v[52:53], v[118:119], v[52:53], v[36:37]
	v_pk_fma_f32 v[54:55], v[116:117], v[54:55], v[38:39]
	v_rsq_f32_e32 v70, v70
	v_cvt_pk_bf16_f32 v52, v52, v53
	v_cvt_pk_bf16_f32 v53, v54, v55
	v_pk_mul_f32 v[54:55], v[76:77], v[126:127] op_sel_hi:[1,0]
	v_pk_mul_f32 v[68:69], v[78:79], v[126:127] op_sel_hi:[1,0]
	v_pk_mul_f32 v[54:55], v[12:13], v[54:55]
	v_pk_mul_f32 v[68:69], v[14:15], v[68:69]
	v_pk_fma_f32 v[54:55], v[96:97], v[54:55], v[44:45]
	v_pk_fma_f32 v[68:69], v[124:125], v[68:69], v[46:47]
	v_cvt_pk_bf16_f32 v54, v54, v55
	v_cvt_pk_bf16_f32 v55, v68, v69
	v_mul_f32_e32 v68, 0x45800000, v70
	v_cndmask_b32_e32 v68, v70, v68, vcc
	v_pk_mul_f32 v[70:71], v[72:73], v[68:69] op_sel_hi:[1,0]
	v_pk_mul_f32 v[72:73], v[74:75], v[68:69] op_sel_hi:[1,0]
	v_pk_mul_f32 v[64:65], v[64:65], v[68:69] op_sel_hi:[1,0]
	v_pk_mul_f32 v[66:67], v[66:67], v[68:69] op_sel_hi:[1,0]
	v_pk_mul_f32 v[60:61], v[60:61], v[68:69] op_sel_hi:[1,0]
	v_pk_mul_f32 v[62:63], v[62:63], v[68:69] op_sel_hi:[1,0]
	v_pk_mul_f32 v[70:71], v[0:1], v[70:71]
	v_pk_mul_f32 v[72:73], v[2:3], v[72:73]
	v_pk_mul_f32 v[64:65], v[4:5], v[64:65]
	v_pk_mul_f32 v[66:67], v[6:7], v[66:67]
	v_pk_mul_f32 v[60:61], v[8:9], v[60:61]
	v_pk_mul_f32 v[62:63], v[10:11], v[62:63]
	v_pk_fma_f32 v[70:71], v[100:101], v[70:71], v[20:21]
	v_pk_fma_f32 v[72:73], v[98:99], v[72:73], v[22:23]
	v_pk_fma_f32 v[64:65], v[110:111], v[64:65], v[28:29]
	v_pk_fma_f32 v[66:67], v[108:109], v[66:67], v[30:31]
	v_pk_fma_f32 v[60:61], v[118:119], v[60:61], v[36:37]
	v_pk_fma_f32 v[62:63], v[116:117], v[62:63], v[38:39]
	v_cvt_pk_bf16_f32 v70, v70, v71
	v_cvt_pk_bf16_f32 v71, v72, v73
	v_cvt_pk_bf16_f32 v64, v64, v65
	v_cvt_pk_bf16_f32 v65, v66, v67
	v_cvt_pk_bf16_f32 v60, v60, v61
	v_cvt_pk_bf16_f32 v61, v62, v63
	global_store_dwordx2 v[104:105], v[48:49], off
	global_store_dwordx2 v[106:107], v[70:71], off
	global_store_dwordx2 v[112:113], v[50:51], off
	global_store_dwordx2 v[114:115], v[64:65], off
	global_store_dwordx2 v[120:121], v[52:53], off
	global_store_dwordx2 v[122:123], v[60:61], off
	global_store_dwordx2 v[102:103], v[54:55], off
	v_pk_mul_f32 v[48:49], v[56:57], v[68:69] op_sel_hi:[1,0]
	v_pk_mul_f32 v[50:51], v[58:59], v[68:69] op_sel_hi:[1,0]
	v_pk_mul_f32 v[48:49], v[12:13], v[48:49]
	v_pk_mul_f32 v[50:51], v[14:15], v[50:51]
	v_pk_fma_f32 v[48:49], v[96:97], v[48:49], v[44:45]
	v_pk_fma_f32 v[50:51], v[124:125], v[50:51], v[46:47]
	v_cvt_pk_bf16_f32 v48, v48, v49
	v_cvt_pk_bf16_f32 v49, v50, v51
	v_lshl_add_u64 v[50:51], v[92:93], 0, v[220:221]
	global_store_dwordx2 v[50:51], v[48:49], off

; DI void phase_final_norm(const Params& p) {
;     ...
;   for (int t = blockIdx.x * 8 + w; t < NB * SEQ; t += gridDim.x * 8) {
;     float* xr = p.out + (size_t)t * D;
;     float4 v[4]; float ss = 0.f;
; #pragma unroll
;     for (int i = 0; i < 4; ++i) { v[i] = *(const float4*)(xr + (i * 64 + lane) * 4); ss += v[i].x * v[i].x + v[i].y * v[i].y + v[i].z * v[i].z + v[i].w * v[i].w; }
;     ss = wave_sum(ss);
;     const float rstd = rsqrtf(ss * (1.f / 1024.f) + EPS);
; #pragma unroll
;     for (int i = 0; i < 4; ++i) {
;       const int k = (i * 64 + lane) * 4;
;       float4 o; o.x = v[i].x * rstd * gg[i].x; o.y = v[i].y * rstd * gg[i].y; o.z = v[i].z * rstd * gg[i].z; o.w = v[i].w * rstd * gg[i].w;
;       *(float4*)(xr + k) = o;
;     }
;   }
.LBB0_1987:
	v_ashrrev_i32_e32 v17, 31, v16
	v_lshlrev_b64 v[28:29], 12, v[16:17]
	v_lshl_add_u64 v[44:45], v[18:19], 0, v[28:29]
	global_load_dwordx4 v[28:31], v[44:45], off nt
	global_load_dwordx4 v[32:35], v[44:45], off offset:1024 nt
	global_load_dwordx4 v[36:39], v[44:45], off offset:2048 nt
	global_load_dwordx4 v[40:43], v[44:45], off offset:3072 nt
	v_add_u32_e32 v16, s4, v16
	v_cmp_lt_i32_e64 s[0:1], s6, v16
	s_or_b64 s[2:3], s[0:1], s[2:3]
	s_waitcnt vmcnt(3)
	v_mov_b32_e32 v48, v29
	s_waitcnt vmcnt(2)
	v_mov_b32_e32 v49, v33
	v_mov_b32_e32 v46, v28
	v_mov_b32_e32 v47, v32
	s_waitcnt vmcnt(1)
	v_mov_b32_e32 v56, v37
	s_waitcnt vmcnt(0)
	v_mov_b32_e32 v57, v41
	v_pk_mul_f32 v[48:49], v[48:49], v[48:49]
	v_mov_b32_e32 v50, v30
	v_mov_b32_e32 v51, v34
	v_mov_b32_e32 v54, v36
	v_mov_b32_e32 v55, v40
	v_pk_mul_f32 v[56:57], v[56:57], v[56:57]
	v_pk_fma_f32 v[46:47], v[46:47], v[46:47], v[48:49]
	v_mov_b32_e32 v52, v31
	v_mov_b32_e32 v53, v35
	v_mov_b32_e32 v58, v38
	v_mov_b32_e32 v59, v42
	v_pk_fma_f32 v[48:49], v[54:55], v[54:55], v[56:57]
	v_pk_fma_f32 v[46:47], v[50:51], v[50:51], v[46:47]
	v_mov_b32_e32 v60, v39
	v_mov_b32_e32 v61, v43
	v_pk_fma_f32 v[48:49], v[58:59], v[58:59], v[48:49]
	v_pk_fma_f32 v[46:47], v[52:53], v[52:53], v[46:47]
	v_pk_fma_f32 v[48:49], v[60:61], v[60:61], v[48:49]
	v_add_f32_e32 v17, v46, v47
	v_add_f32_e32 v17, v17, v48
	v_add_f32_e32 v17, v17, v49
	ds_bpermute_b32 v27, v20, v17
	s_waitcnt lgkmcnt(0)
	v_add_f32_e32 v17, v17, v27
	ds_bpermute_b32 v27, v21, v17
	s_waitcnt lgkmcnt(0)
	v_add_f32_e32 v17, v17, v27
	ds_bpermute_b32 v27, v22, v17
	s_waitcnt lgkmcnt(0)
	v_add_f32_e32 v17, v17, v27
	ds_bpermute_b32 v27, v23, v17
	s_waitcnt lgkmcnt(0)
	v_add_f32_e32 v17, v17, v27
	ds_bpermute_b32 v27, v24, v17
	s_waitcnt lgkmcnt(0)
	v_add_f32_e32 v17, v17, v27
	ds_bpermute_b32 v27, v25, v17
	s_waitcnt lgkmcnt(0)
	v_add_f32_e32 v17, v17, v27
	v_fmamk_f32 v17, v17, 0x3a800000, v26
	v_mul_f32_e32 v27, 0x4b800000, v17
	v_cmp_gt_f32_e32 vcc, s5, v17
	s_nop 1
	v_cndmask_b32_e32 v17, v17, v27, vcc
	v_rsq_f32_e32 v17, v17
	s_nop 0
	v_mul_f32_e32 v27, 0x45800000, v17
	v_cndmask_b32_e32 v46, v17, v27, vcc
	v_pk_mul_f32 v[28:29], v[28:29], v[46:47] op_sel_hi:[1,0]
	v_pk_mul_f32 v[30:31], v[30:31], v[46:47] op_sel_hi:[1,0]
	v_pk_mul_f32 v[32:33], v[32:33], v[46:47] op_sel_hi:[1,0]
	v_pk_mul_f32 v[34:35], v[34:35], v[46:47] op_sel_hi:[1,0]
	v_pk_mul_f32 v[36:37], v[36:37], v[46:47] op_sel_hi:[1,0]
	v_pk_mul_f32 v[38:39], v[38:39], v[46:47] op_sel_hi:[1,0]
	v_pk_mul_f32 v[40:41], v[40:41], v[46:47] op_sel_hi:[1,0]
	v_pk_mul_f32 v[42:43], v[42:43], v[46:47] op_sel_hi:[1,0]
	v_pk_mul_f32 v[28:29], v[0:1], v[28:29]
	v_pk_mul_f32 v[30:31], v[2:3], v[30:31]
	v_pk_mul_f32 v[32:33], v[4:5], v[32:33]
	v_pk_mul_f32 v[34:35], v[6:7], v[34:35]
	v_pk_mul_f32 v[36:37], v[8:9], v[36:37]
	v_pk_mul_f32 v[38:39], v[10:11], v[38:39]
	v_pk_mul_f32 v[40:41], v[12:13], v[40:41]
	v_pk_mul_f32 v[42:43], v[14:15], v[42:43]
	global_store_dwordx4 v[44:45], v[28:31], off
	global_store_dwordx4 v[44:45], v[32:35], off offset:1024
	global_store_dwordx4 v[44:45], v[36:39], off offset:2048
	global_store_dwordx4 v[44:45], v[40:43], off offset:3072
	s_andn2_b64 exec, exec, s[2:3]
	s_cbranch_execnz .LBB0_1987
